# fused out-proj epilogues: four exchange partials loaded together; EpiOutMod next-layer vector loads issued before the counter spin
# baseline (speedup 1.0000x reference)
;     __device__ __forceinline__ void fused(f32x4 (&acc)[2][2][4][2], const Unit& u, int wr, int wc, int fr, int fq, PG8_LAS unsigned char* lds, int wid, int lane) const {
;     ...
;         if (t == 0) {
;             __hip_atomic_fetch_add(cnt + 64 * u.pm, 1u, __ATOMIC_RELAXED, __HIP_MEMORY_SCOPE_AGENT);
;             unsigned sp = 0;
;             while (__hip_atomic_load(cnt + 64 * u.pm, __ATOMIC_RELAXED, __HIP_MEMORY_SCOPE_AGENT) < 4u) { __builtin_amdgcn_s_sleep(1); if (++sp > (1u << 22)) break; }
;         }
;         f32x4 mul[2][2], add[2][2];
; #pragma unroll
;         for (int bj = 0; bj < 2; ++bj)
; #pragma unroll
;             for (int n = 0; n < 2; ++n) { const int c = col0 + bj * HALF + 16 * n;
;                 mul[bj][n] = *(const f32x4*)(nw + c) * (*(const f32x4*)(modf2 + (size_t)b * 3072 + 1024 + c) + 1.f); add[bj][n] = *(const f32x4*)(modf2 + (size_t)b * 3072 + c); }
.LBB0_633:
	s_or_b64 exec, exec, s[30:31]
	s_waitcnt vmcnt(0)
	v_cmp_eq_u32_e32 vcc, 0, v208
	s_barrier
	v_readlane_b32 s16, v254, 37
	s_add_u32 s26, s16, s34
	v_readlane_b32 s16, v254, 38
	s_addc_u32 s27, s16, s33
	v_readlane_b32 s38, v254, 35
	s_add_u32 s30, s26, 0x1000
	v_lshlrev_b64 v[132:133], 2, v[180:181]
	v_readlane_b32 s39, v254, 36
	s_addc_u32 s31, s27, 0
	v_lshl_add_u64 v[136:137], s[26:27], 0, v[132:133]
	v_lshl_add_u64 v[134:135], s[38:39], 0, v[132:133]
	global_load_dwordx4 v[148:151], v[134:135], off
	v_lshl_add_u64 v[134:135], s[30:31], 0, v[132:133]
	v_or_b32_e32 v132, 16, v180
	v_ashrrev_i32_e32 v133, 31, v132
	v_lshlrev_b64 v[132:133], 2, v[132:133]
	global_load_dwordx4 v[152:155], v[134:135], off
	global_load_dwordx4 v[140:143], v[136:137], off
	v_lshl_add_u64 v[134:135], s[38:39], 0, v[132:133]
	v_lshl_add_u64 v[132:133], s[30:31], 0, v[132:133]
	global_load_dwordx4 v[160:163], v[132:133], off
	v_or_b32_e32 v132, 0x80, v180
	v_ashrrev_i32_e32 v133, 31, v132
	v_or_b32_e32 v138, 0x90, v180
	v_lshlrev_b64 v[132:133], 2, v[132:133]
	v_ashrrev_i32_e32 v139, 31, v138
	global_load_dwordx4 v[156:159], v[134:135], off
	v_lshl_add_u64 v[134:135], s[38:39], 0, v[132:133]
	v_lshl_add_u64 v[132:133], s[30:31], 0, v[132:133]
	v_lshlrev_b64 v[138:139], 2, v[138:139]
	global_load_dwordx4 v[164:167], v[134:135], off
	global_load_dwordx4 v[168:171], v[132:133], off
	global_load_dwordx4 v[144:147], v[136:137], off offset:64
	s_nop 0
	global_load_dwordx4 v[132:135], v[136:137], off offset:512
	v_lshl_add_u64 v[172:173], s[38:39], 0, v[138:139]
	v_lshl_add_u64 v[138:139], s[30:31], 0, v[138:139]
	global_load_dwordx4 v[172:175], v[172:173], off
	s_nop 0
	global_load_dwordx4 v[176:179], v[138:139], off
	s_nop 0
	global_load_dwordx4 v[136:139], v[136:137], off offset:576
	s_and_saveexec_b64 s[26:27], vcc
	s_cbranch_execz .LBB0_644
	s_lshl_b32 s30, s20, 6
	s_mov_b64 s[38:39], exec
	s_ashr_i32 s31, s30, 31
	s_lshl_b64 s[30:31], s[30:31], 2
	v_readlane_b32 s16, v254, 41
	v_mbcnt_lo_u32_b32 v213, s38, 0
	s_add_u32 s30, s16, s30
	v_readlane_b32 s16, v254, 42
	v_mbcnt_hi_u32_b32 v213, s39, v213
	s_addc_u32 s31, s16, s31
	v_cmp_eq_u32_e32 vcc, 0, v213
	s_and_saveexec_b64 s[40:41], vcc
	s_cbranch_execz .LBB0_636
	s_bcnt1_i32_b64 s16, s[38:39]
	v_mov_b32_e32 v213, s16
	global_atomic_add v189, v213, s[30:31]

;     __device__ __forceinline__ void fused(f32x4 (&acc)[2][2][4][2], const Unit& u, int wr, int wc, int fr, int fq, PG8_LAS unsigned char* lds, int wid, int lane) const {
;     ...
;             unsigned sp = 0;
;             while (__hip_atomic_load(cnt + 64 * u.pm, __ATOMIC_RELAXED, __HIP_MEMORY_SCOPE_AGENT) < 4u) { __builtin_amdgcn_s_sleep(1); if (++sp > (1u << 22)) break; }
;         }
;         f32x4 mul[2][2], add[2][2];
; #pragma unroll
;         for (int bj = 0; bj < 2; ++bj)
; #pragma unroll
;             for (int n = 0; n < 2; ++n) { const int c = col0 + bj * HALF + 16 * n;
;                 mul[bj][n] = *(const f32x4*)(nw + c) * (*(const f32x4*)(modf2 + (size_t)b * 3072 + 1024 + c) + 1.f); add[bj][n] = *(const f32x4*)(modf2 + (size_t)b * 3072 + c); }
;         __syncthreads();
;         if (t < 256) { float tot = 0.f;
; #pragma unroll
;             for (int pn2 = 0; pn2 < 4; ++pn2) tot += __hip_atomic_load(xch + ((size_t)u.pm * 256 + t) * 4 + pn2, __ATOMIC_RELAXED, __HIP_MEMORY_SCOPE_AGENT);
;             S[t] = rsqrtf(tot * (1.f / 1024.f) + 1e-6f); }
.LBB0_638:
	global_load_dword v213, v189, s[30:31] sc1
	s_mov_b64 s[38:39], -1
	s_waitcnt vmcnt(0)
	v_cmp_lt_u32_e32 vcc, 3, v213
	s_cbranch_vccnz .LBB0_637
	s_sleep 1
	global_load_dword v213, v189, s[30:31] sc1
	s_waitcnt vmcnt(0)
	v_cmp_gt_u32_e32 vcc, 4, v213
	s_cbranch_vccz .LBB0_637
	s_sleep 1
	global_load_dword v213, v189, s[30:31] sc1
	s_waitcnt vmcnt(0)
	v_cmp_gt_u32_e32 vcc, 4, v213
	s_cbranch_vccz .LBB0_637
	s_sleep 1
	global_load_dword v213, v189, s[30:31] sc1
	s_waitcnt vmcnt(0)
	v_cmp_gt_u32_e32 vcc, 4, v213
	s_cbranch_vccz .LBB0_637
	s_sleep 1
	global_load_dword v213, v189, s[30:31] sc1
	s_waitcnt vmcnt(0)
	v_cmp_gt_u32_e32 vcc, 4, v213
	s_cbranch_vccz .LBB0_637
	s_add_i32 s16, s16, -5
	s_cmp_eq_u32 s16, 0
	s_cselect_b64 s[38:39], -1, 0
	s_sleep 1
	s_branch .LBB0_637
.LBB0_644:
	s_or_b64 exec, exec, s[26:27]
	s_barrier
	s_and_saveexec_b64 s[26:27], s[36:37]
	s_cbranch_execz .LBB0_646
	s_ashr_i32 s21, s20, 31
	s_lshl_b64 s[20:21], s[20:21], 12
	v_readlane_b32 s16, v254, 39
	s_add_u32 s20, s16, s20
	v_readlane_b32 s16, v254, 40
	s_addc_u32 s21, s16, s21
	v_lshl_add_u64 v[194:195], v[208:209], 4, s[20:21]
	global_load_dword v188, v[194:195], off sc1
	global_load_dword v196, v[194:195], off offset:4 sc1
	global_load_dword v212, v[194:195], off offset:8 sc1
	global_load_dword v194, v[194:195], off offset:12 sc1
	s_waitcnt vmcnt(3)
	v_add_f32_e32 v188, 0, v188
	s_waitcnt vmcnt(2)
	v_add_f32_e32 v188, v188, v196
	s_waitcnt vmcnt(1)
	v_add_f32_e32 v188, v188, v212
	s_waitcnt vmcnt(0)
	v_add_f32_e32 v188, v188, v194
	v_fmamk_f32 v188, v188, 0x3a800000, v190
	v_cmp_gt_f32_e32 vcc, s15, v188
	v_mul_f32_e32 v194, 0x4b800000, v188
	s_nop 0
	v_cndmask_b32_e32 v188, v188, v194, vcc
	v_rsq_f32_e32 v188, v188
	s_nop 0
	v_mul_f32_e32 v194, 0x45800000, v188
	v_cndmask_b32_e32 v188, v188, v194, vcc
	v_lshl_add_u32 v194, v208, 2, 0
	ds_write_b32 v194, v188 offset:4096

;     __device__ __forceinline__ void fused(f32x4 (&acc)[2][2][4][2], const Unit& u, int wr, int wc, int fr, int fq, PG8_LAS unsigned char* lds, int wid, int lane) const {
;     ...
;         if (t < 256) { float tot = 0.f;
; #pragma unroll
;             for (int pn2 = 0; pn2 < 4; ++pn2) tot += __hip_atomic_load(xch + ((size_t)u.pm * 256 + t) * 4 + pn2, __ATOMIC_RELAXED, __HIP_MEMORY_SCOPE_AGENT);
;             S[t] = rsqrtf(tot * (1.f / 1024.f) + 1e-6f); }
.LBB0_698:
	s_or_b64 exec, exec, s[18:19]
	s_barrier
	s_and_saveexec_b64 s[18:19], s[36:37]
	s_cbranch_execz .LBB0_700
	s_ashr_i32 s21, s20, 31
	s_lshl_b64 s[20:21], s[20:21], 12
	v_readlane_b32 s2, v254, 43
	s_add_u32 s20, s2, s20
	v_readlane_b32 s2, v254, 44
	s_addc_u32 s21, s2, s21
	v_lshl_add_u64 v[6:7], v[4:5], 4, s[20:21]
	global_load_dword v5, v[6:7], off sc1
	global_load_dword v8, v[6:7], off offset:4 sc1
	global_load_dword v9, v[6:7], off offset:8 sc1
	global_load_dword v6, v[6:7], off offset:12 sc1
	v_lshl_add_u32 v4, v4, 2, 0
	s_waitcnt vmcnt(3)
	v_add_f32_e32 v5, 0, v5
	s_waitcnt vmcnt(2)
	v_add_f32_e32 v5, v5, v8
	s_waitcnt vmcnt(1)
	v_add_f32_e32 v5, v5, v9
	s_waitcnt vmcnt(0)
	v_add_f32_e32 v5, v5, v6
	v_fmamk_f32 v5, v5, 0x3a800000, v190
	v_cmp_gt_f32_e32 vcc, s15, v5
	v_mul_f32_e32 v6, 0x4b800000, v5
	s_nop 0
	v_cndmask_b32_e32 v5, v5, v6, vcc
	v_rsq_f32_e32 v5, v5
	s_nop 0
	v_mul_f32_e32 v6, 0x45800000, v5
	v_cndmask_b32_e32 v5, v5, v6, vcc
	ds_write_b32 v4, v5 offset:4096
